# XCD-local seams (G4->G5 both layers, G5->G6 layer 0): leader skips the cross-XCD hop when census says XCC==bx%8; plus barrier-shadow weight prefetch
# speedup vs baseline: 1.0036x; 1.0036x over previous
; #define LAS __attribute__((address_space(3)))
; __device__ __forceinline__ unsigned xb_ld(unsigned* p)              { return __hip_atomic_load(p, __ATOMIC_RELAXED, __HIP_MEMORY_SCOPE_AGENT); }
; __device__ __forceinline__ unsigned xb_add(unsigned* p, unsigned v) { return __hip_atomic_fetch_add(p, v, __ATOMIC_RELAXED, __HIP_MEMORY_SCOPE_AGENT); }
; __device__ __forceinline__ unsigned xb_xcc_id() { return (unsigned)__builtin_amdgcn_s_getreg((3 << 11) | 20) & 0xFu; }
; __device__ __forceinline__ XcdBarrier xcd_barrier_post(unsigned* bar, volatile LAS unsigned* st) {
;     XcdBarrier b; b.bar = bar; b.x = xb_xcc_id(); b.st = st;
;     if (threadIdx.x == 0) (void)xb_add(&bar[XB_XCNT(b.x)], 1u);
;     return b;
; }
; __device__ __forceinline__ void xcd_barrier_complete(unsigned* bar, unsigned x, unsigned& nloc, unsigned& nx) {
;     const unsigned G = gridDim.x * gridDim.y * gridDim.z;
;     unsigned sum, cnt, mine, sp = 0u;
;     for (;;) {
;         sum = 0u; cnt = 0u; mine = 0u;
; #pragma unroll
;         for (unsigned j = 0; j < 16; ++j) { const unsigned c = xb_ld(&bar[XB_XCNT(j)]); sum += c; cnt += (c > 0u) ? 1u : 0u; mine = (j == x) ? c : mine; }
;         if (sum == G) break;
;         __builtin_amdgcn_s_sleep(1);
;         if ((++sp & 255u) == 0u) { if (xb_ld(&bar[XB_TMO])) break; if (sp > XB_SPIN_CAP) { atomicAdd(&bar[XB_TMO], 1u); break; } }
;     }
;     nloc = mine > 0u ? mine : 1u; nx = cnt > 0u ? cnt : 1u;
; }
; __device__ __forceinline__ void xcd_barrier(const XcdBarrier& b) {
;     asm volatile("s_waitcnt vmcnt(0)" ::: "memory");
;     __syncthreads();
;     if (threadIdx.x == 0) {
;         unsigned* bar = b.bar;
;         __builtin_amdgcn_s_waitcnt(0);
;         unsigned nloc = b.st[0], nx = b.st[1];
;         if (nloc == 0u) { xcd_barrier_complete(bar, b.x, nloc, nx); b.st[0] = nloc; b.st[1] = nx; }
.LBB0_150:
	s_or_b64 exec, exec, s[8:9]
	s_getreg_b32 s3, hwreg(HW_REG_XCC_ID, 0, 4)
	v_cmp_eq_u32_e64 s[4:5], 0, v184
	s_mov_b64 s[0:1], exec
	s_nop 0
	v_writelane_b32 v252, s4, 32
	s_nop 1
	v_writelane_b32 v252, s5, 33
	s_and_b64 s[4:5], s[0:1], s[4:5]
	s_mov_b64 exec, s[4:5]
	s_cbranch_execz .LBB0_153
	s_mov_b64 s[4:5], exec
	v_mbcnt_lo_u32_b32 v0, s4, 0
	v_mbcnt_hi_u32_b32 v0, s5, v0
	v_cmp_eq_u32_e32 vcc, 0, v0
	s_and_b64 s[6:7], exec, vcc
	s_mov_b64 exec, s[6:7]
	s_cbranch_execz .LBB0_153
	s_lshl_b32 s3, s3, 8
	s_and_b32 s3, s3, 0xf00
	s_bcnt1_i32_b64 s4, s[4:5]
	v_mov_b32_e32 v0, s3
	v_mov_b32_e32 v1, s4
	global_atomic_add v0, v1, s[96:97] offset:1024
	s_lshr_b32 s4, s3, 8
	s_and_b32 s5, s2, 7
	s_cmp_eq_u32 s4, s5
	s_cbranch_scc1 .Lxm_same
	v_mov_b32_e32 v0, 0x300
	global_atomic_add v0, v1, s[96:97]
.Lxm_same:
.LBB0_153:
	s_or_b64 exec, exec, s[0:1]
	s_getreg_b32 s3, hwreg(HW_REG_XCC_ID, 0, 4)
	s_waitcnt vmcnt(0)
	s_waitcnt lgkmcnt(0)
	s_barrier
	s_mov_b64 s[0:1], exec
	v_readlane_b32 s4, v252, 32
	v_readlane_b32 s5, v252, 33
	s_and_b64 s[4:5], s[0:1], s[4:5]
	s_mov_b64 exec, s[4:5]
	s_cbranch_execz .LBB0_205
	s_add_i32 s4, 0, 0x23fc0
	v_mov_b32_e32 v0, s4
	s_waitcnt vmcnt(0) expcnt(0) lgkmcnt(0)
	ds_read_b32 v2, v0
	s_add_i32 s4, 0, 0x23fc4
	v_mov_b32_e32 v0, s4
	ds_read_b32 v0, v0
	s_and_b32 s3, s3, 15
	s_waitcnt lgkmcnt(1)
	v_cmp_ne_u32_e32 vcc, 0, v2
	s_cbranch_vccnz .LBB0_169
	s_add_u32 s4, s70, 0x4200
	s_addc_u32 s5, s71, 0
	s_add_u32 s6, s70, 0x4400
	s_addc_u32 s7, s71, 0
	s_add_u32 s8, s70, 0x4500
	s_addc_u32 s9, s71, 0
	s_add_u32 s10, s70, 0x4600
	s_addc_u32 s11, s71, 0
	s_add_u32 s12, s70, 0x4700
	s_addc_u32 s13, s71, 0
	s_add_u32 s14, s70, 0x4800
	s_addc_u32 s15, s71, 0
	s_add_u32 s16, s70, 0x4900
	s_addc_u32 s17, s71, 0
	s_add_u32 s18, s70, 0x4a00
	s_addc_u32 s19, s71, 0
	s_add_u32 s20, s70, 0x4b00
	s_addc_u32 s21, s71, 0
	s_add_u32 s22, s70, 0x4c00
	s_addc_u32 s23, s71, 0
	s_add_u32 s24, s70, 0x4d00
	s_addc_u32 s25, s71, 0
	s_add_u32 s26, s70, 0x4e00
	s_addc_u32 s27, s71, 0
	s_add_u32 s28, s70, 0x4f00
	s_addc_u32 s29, s71, 0
	s_add_u32 s36, s70, 0x5000
	s_addc_u32 s37, s71, 0
	s_add_u32 s38, s70, 0x5100
	s_addc_u32 s39, s71, 0
	s_add_u32 s48, s70, 0x5200
	s_addc_u32 s49, s71, 0
	s_mul_i32 s33, s35, s58
	s_add_u32 s50, s70, 0x5300
	s_mul_i32 s33, s33, s34
	s_addc_u32 s51, s71, 0
	s_mov_b32 s60, 1
	v_mov_b32_e32 v17, 0
	s_branch .LBB0_157

; __device__ __forceinline__ unsigned xb_add(unsigned* p, unsigned v) { return __hip_atomic_fetch_add(p, v, __ATOMIC_RELAXED, __HIP_MEMORY_SCOPE_AGENT); }
; __device__ __forceinline__ void xcd_barrier(const XcdBarrier& b) {
;     ...
;         const unsigned old = xb_add(&bar[XB_XSUB(b.x)], 1u);
;         const unsigned gen = old / nloc;
;         if (old + 1u == (gen + 1u) * nloc) {
.LBB0_818:
	s_mov_b64 s[8:9], exec
	s_lshl_b32 s6, s12, 8
	v_mbcnt_lo_u32_b32 v0, s8, 0
	s_add_u32 s6, s96, s6
	v_mbcnt_hi_u32_b32 v0, s9, v0
	s_addc_u32 s7, s97, 0
	v_cmp_eq_u32_e32 vcc, 0, v0
	s_and_saveexec_b64 s[10:11], vcc
	s_cbranch_execz .LBB0_820
	s_bcnt1_i32_b64 s8, s[8:9]
	v_mov_b32_e32 v20, s8
	v_mov_b32_e32 v21, 0x1000
	global_load_dword v23, v1, s[96:97] offset:768 sc1
	global_atomic_add v20, v21, v20, s[6:7] offset:1024 sc0

; __device__ __forceinline__ unsigned xb_ld(unsigned* p)              { return __hip_atomic_load(p, __ATOMIC_RELAXED, __HIP_MEMORY_SCOPE_AGENT); }
; __device__ __forceinline__ unsigned xb_add(unsigned* p, unsigned v) { return __hip_atomic_fetch_add(p, v, __ATOMIC_RELAXED, __HIP_MEMORY_SCOPE_AGENT); }
; #define XB_SPIN(cond, bar) do { unsigned _sp = 0; while (cond) { __builtin_amdgcn_s_sleep(1); \
;     if ((++_sp & 255u) == 0u) { if (xb_ld(&(bar)[XB_TMO])) break; if (_sp > XB_SPIN_CAP) { atomicAdd(&(bar)[XB_TMO], 1u); break; } } } } while (0)
; __device__ __forceinline__ void xcd_barrier(const XcdBarrier& b) {
;     ...
;         if (old + 1u == (gen + 1u) * nloc) {
;             __builtin_amdgcn_fence(__ATOMIC_RELEASE, "agent");
;             asm volatile("s_waitcnt vmcnt(0)" ::: "memory");
;             const unsigned og = xb_add(&bar[XB_TOP], 1u);
;             const unsigned tg = og / nx;
;             if (og + 1u == (tg + 1u) * nx) xb_add(&bar[XB_TOPGEN], 1u);
;             else XB_SPIN(xb_ld(&bar[XB_TOPGEN]) == tg, bar);
;             __builtin_amdgcn_fence(__ATOMIC_ACQUIRE, "agent");
;             xb_add(&bar[XB_XGEN(b.x)], 1u);
.LBB0_834:
	s_andn2_saveexec_b64 s[8:9], s[8:9]
	s_cbranch_execz .LBB0_854
	s_mov_b64 s[8:9], exec
	buffer_wbl2 sc1
	buffer_inv sc1
	s_waitcnt lgkmcnt(0)
	s_waitcnt vmcnt(0)
	v_readfirstlane_b32 s10, v23
	s_cmp_eq_u32 s10, 0
	s_cbranch_scc1 .LBB0_851
	v_mbcnt_lo_u32_b32 v0, s8, 0
	v_mbcnt_hi_u32_b32 v0, s9, v0
	v_cmp_eq_u32_e32 vcc, 0, v0
	s_and_saveexec_b64 s[10:11], vcc
	s_cbranch_execz .LBB0_837
	s_bcnt1_i32_b64 s8, s[8:9]
	v_mov_b32_e32 v3, s8
	v_readlane_b32 s8, v253, 26
	v_readlane_b32 s9, v253, 27
	s_nop 4
	global_atomic_add v3, v1, v3, s[8:9] sc0

; __device__ __forceinline__ unsigned xb_add(unsigned* p, unsigned v) { return __hip_atomic_fetch_add(p, v, __ATOMIC_RELAXED, __HIP_MEMORY_SCOPE_AGENT); }
; __device__ __forceinline__ void xcd_barrier(const XcdBarrier& b) {
;     ...
;         const unsigned old = xb_add(&bar[XB_XSUB(b.x)], 1u);
;         const unsigned gen = old / nloc;
;         if (old + 1u == (gen + 1u) * nloc) {
.LBB0_893:
	s_mov_b64 s[6:7], exec
	s_lshl_b32 s4, s10, 8
	v_mbcnt_lo_u32_b32 v0, s6, 0
	s_add_u32 s4, s96, s4
	v_mbcnt_hi_u32_b32 v0, s7, v0
	s_addc_u32 s5, s97, 0
	v_cmp_eq_u32_e32 vcc, 0, v0
	s_and_saveexec_b64 s[8:9], vcc
	s_cbranch_execz .LBB0_895
	s_bcnt1_i32_b64 s6, s[6:7]
	v_mov_b32_e32 v20, s6
	v_mov_b32_e32 v21, 0x1000
	global_load_dword v23, v1, s[96:97] offset:768 sc1
	global_atomic_add v20, v21, v20, s[4:5] offset:1024 sc0

; __device__ __forceinline__ unsigned xb_ld(unsigned* p)              { return __hip_atomic_load(p, __ATOMIC_RELAXED, __HIP_MEMORY_SCOPE_AGENT); }
; __device__ __forceinline__ unsigned xb_add(unsigned* p, unsigned v) { return __hip_atomic_fetch_add(p, v, __ATOMIC_RELAXED, __HIP_MEMORY_SCOPE_AGENT); }
; #define XB_SPIN(cond, bar) do { unsigned _sp = 0; while (cond) { __builtin_amdgcn_s_sleep(1); \
;     if ((++_sp & 255u) == 0u) { if (xb_ld(&(bar)[XB_TMO])) break; if (_sp > XB_SPIN_CAP) { atomicAdd(&(bar)[XB_TMO], 1u); break; } } } } while (0)
; __device__ __forceinline__ void xcd_barrier(const XcdBarrier& b) {
;     ...
;         if (old + 1u == (gen + 1u) * nloc) {
;             __builtin_amdgcn_fence(__ATOMIC_RELEASE, "agent");
;             asm volatile("s_waitcnt vmcnt(0)" ::: "memory");
;             const unsigned og = xb_add(&bar[XB_TOP], 1u);
;             const unsigned tg = og / nx;
;             if (og + 1u == (tg + 1u) * nx) xb_add(&bar[XB_TOPGEN], 1u);
;             else XB_SPIN(xb_ld(&bar[XB_TOPGEN]) == tg, bar);
;             __builtin_amdgcn_fence(__ATOMIC_ACQUIRE, "agent");
;             xb_add(&bar[XB_XGEN(b.x)], 1u);
.LBB0_909:
	s_andn2_saveexec_b64 s[6:7], s[6:7]
	s_cbranch_execz .LBB0_929
	s_mov_b64 s[6:7], exec
	buffer_wbl2 sc1
	buffer_inv sc1
	s_waitcnt lgkmcnt(0)
	s_waitcnt vmcnt(0)
	v_readfirstlane_b32 s8, v23
	v_readlane_b32 s9, v255, 35
	s_or_b32 s8, s8, s9
	s_cmp_eq_u32 s8, 0
	s_cbranch_scc1 .LBB0_926
	v_mbcnt_lo_u32_b32 v0, s6, 0
	v_mbcnt_hi_u32_b32 v0, s7, v0
	v_cmp_eq_u32_e32 vcc, 0, v0
	s_and_saveexec_b64 s[8:9], vcc
	s_cbranch_execz .LBB0_912
	s_bcnt1_i32_b64 s6, s[6:7]
	v_mov_b32_e32 v3, s6
	v_readlane_b32 s6, v253, 26
	v_readlane_b32 s7, v253, 27
	s_nop 4
	global_atomic_add v3, v1, v3, s[6:7] sc0
